# v41 + same 4x8 per-round tile order for P13 FFN2-down fp8 GEMM (hidden read once from HBM)
# baseline (speedup 1.0000x reference)
.LBB0_2700:
	s_add_i32 s0, s1, s2
	s_and_b32 s98, s0, 3
	s_bfe_u32 s99, s0, 0x10005
	s_lshl_b32 s99, s99, 2
	s_or_b32 s98, s98, s99
	s_bfe_u32 s99, s0, 0x30002
	s_lshl_b32 s99, s99, 3
	s_or_b32 s98, s98, s99
	s_andn2_b32 s0, s0, 63
	s_or_b32 s0, s0, s98
	s_ashr_i32 s1, s0, 31
	s_lshr_b32 s1, s1, 25
	s_add_i32 s1, s0, s1
	s_ashr_i32 s2, s1, 7
	s_and_b32 s1, s1, 0xff80
	s_sub_i32 s0, s0, s1
	s_bfe_i32 s1, s0, 0x80000
	s_bfe_u32 s1, s1, 0x3000c
	s_add_i32 s1, s0, s1
	s_bfe_i32 s3, s1, 0x80000
	s_and_b32 s1, s1, 0xf8
	s_sub_i32 s0, s0, s1
	s_lshl_b32 s2, s2, 3
	s_sext_i32_i16 s3, s3
	s_sext_i32_i8 s0, s0
	s_add_i32 s4, s2, s0
	s_ashr_i32 s2, s3, 3

.LBB0_2712:
	s_ashr_i32 s5, s5, 3
	s_add_i32 s5, s17, s5
	s_and_b32 s98, s5, 3
	s_bfe_u32 s99, s5, 0x10005
	s_lshl_b32 s99, s99, 2
	s_or_b32 s98, s98, s99
	s_bfe_u32 s99, s5, 0x30002
	s_lshl_b32 s99, s99, 3
	s_or_b32 s98, s98, s99
	s_andn2_b32 s5, s5, 63
	s_or_b32 s5, s5, s98
	s_ashr_i32 s14, s5, 31
	s_lshr_b32 s14, s14, 25
	s_add_i32 s14, s5, s14
	s_ashr_i32 s15, s14, 7
	s_lshl_b32 s15, s15, 3
	s_sub_i32 s16, 32, s15
	s_min_i32 s16, s16, 8
	s_abs_i32 s17, s16
	v_cvt_f32_u32_e32 v2, s17
	s_sub_i32 s19, 0, s17
	s_and_b32 s14, s14, 0xffffff80
	s_sub_i32 s5, s5, s14
	v_rcp_iflag_f32_e32 v2, v2
	s_abs_i32 s14, s5
	s_xor_b32 s18, s5, s16
	s_ashr_i32 s18, s18, 31
	v_mul_f32_e32 v2, 0x4f7ffffe, v2
	v_cvt_u32_f32_e32 v2, v2
	s_nop 0
	v_readfirstlane_b32 s20, v2
	s_mul_i32 s19, s19, s20
	s_mul_hi_u32 s19, s20, s19
	s_add_i32 s20, s20, s19
	s_mul_hi_u32 s19, s14, s20
	s_mul_i32 s20, s19, s17
	s_sub_i32 s14, s14, s20
	s_add_i32 s21, s19, 1
	s_sub_i32 s20, s14, s17
	s_cmp_ge_u32 s14, s17
	s_cselect_b32 s19, s21, s19
	s_cselect_b32 s14, s20, s14
	s_add_i32 s20, s19, 1
	s_cmp_ge_u32 s14, s17
	s_cselect_b32 s14, s20, s19
	s_xor_b32 s14, s14, s18
	s_sub_i32 s14, s14, s18
	s_mul_i32 s16, s14, s16
	s_sub_i32 s5, s5, s16
	s_add_i32 s16, s15, s5
